# diff-attn loop: hoist minit copies out of tile loop, drop 16 v_mov_b64 per 2 tiles
# speedup vs baseline: 1.0091x; 1.0091x over previous
; __device__ __forceinline__ unsigned cvtb(float lo, float hi) { const f32x2 v = {lo, hi}; const bf16x2v_t r = __builtin_convertvector(v, bf16x2v_t); return __builtin_bit_cast(unsigned, r); }
; __device__ __forceinline__ int v_st(int k, int c) { const int kk = k; return ((kk >> 3) * 4 + (c >> 5)) * 512 + ((kk & 7) * 32 + (c & 31)) * 2; }
; template <int NQK, int SD, bool MI> ...
;     ...
;   const bf16_t* Qw = Qb + (long)(wid * 32 + r32) * ldq + hi * 8;
; #pragma unroll
;   for (int d0 = 0; d0 < NQK; ++d0) qr[d0] = *reinterpret_cast<const bf16x8*>(Qw + d0 * 16);
;   f32x16 minit = {}; float Mref = 0.f; const float thr2 = 8.f * 1.4426950408889634f;
;   if constexpr (MI) {
; #pragma unroll
;     for (int d0 = 0; d0 < NQK; ++d0) { u32x4 w = *reinterpret_cast<u32x4*>(&qr[d0]);
; #pragma unroll
;       for (int e = 0; e < 4; ++e) { const float lo = __uint_as_float(w[e] << 16) * C, hi2 = __uint_as_float(w[e] & 0xffff0000u) * C; w[e] = cvtb(lo, hi2); }
;       qr[d0] = *reinterpret_cast<bf16x8*>(&w); }
;   }
;   constexpr bool RECOMP = false;
;   const int p_voffV = ((tid >> 4) * ldv + (tid & 15) * 8) * 2, p_vstV = v_st(tid >> 4, (tid & 15) * 8);
;   const int p_voffK = ((tid >> 3) * ldk + (tid & 7) * 8) * 2, p_ldsK = (tid >> 3) * KROW + (tid & 7) * 16;
;     ...
;   const auto rK = __builtin_amdgcn_make_buffer_rsrc((void*)Kh, 0, 0x7ffffff0, 0x00020000);
;   const auto rV = __builtin_amdgcn_make_buffer_rsrc((void*)Vh, 0, 0x7ffffff0, 0x00020000);
;   const int vb0 = (int)(uintptr_t)V_lds + v_rd_base(lane);
;   struct { u32x4 vs0, vs1; u32x4 ks[NP]; } sr_[SD];
;     ...
;   f32x16 pA0, pA1, pB0, pB1; float mnA, mnB, alA, alB; bf16x8 pa0, pa1, pa2, pa3; const int NT = seq / 64;
;   constexpr int SE = 0, SO = SD - 1;
;   if (__builtin_amdgcn_readfirstlane(tid) >= 256) __builtin_amdgcn_s_setprio(1);
;   __syncthreads();
;     ...
;   SLOAD(SE, 0); asm volatile("s_waitcnt vmcnt(0)" ::: "memory"); SWRITE(0, SE); __syncthreads();
;   if constexpr (MI) { qkt_mi<NQK>(pA0, pA1, K_lds, qr, r32, hi, minit); decide_mi(pA0, pA1, minit, Mref, alA, thr2, true);
; #pragma unroll
;     for (int r = 0; r < 16; ++r) pA0[r] = __builtin_amdgcn_exp2f(pA0[r]); }
;   else { qkt<NQK>(pA0, pA1, K_lds, qr, r32, hi); partialSM(pA0, pA1, m_reg, mnA, alA, C, thr); }
;   SLOAD(SO, 64); if constexpr (SD == 2) { if (2 < NT) SLOAD(SE, 2 * 64); }
.LBB0_1285:
	s_lshl_b32 s7, s6, 1
	s_add_u32 s36, s25, s7
	s_addc_u32 s7, s44, 0
	s_and_b32 s6, s6, 0x180
	v_ashrrev_i32_e32 v32, 4, v16
	v_lshlrev_b32_e32 v33, 3, v16
	s_lshl_b32 s6, s6, 1
	v_and_b32_e32 v18, 0x78, v33
	v_lshlrev_b32_e32 v19, 10, v32
	s_add_u32 s28, s90, s6
	v_lshl_or_b32 v216, v18, 1, v19
	v_lshlrev_b32_e32 v18, 4, v16
	s_addc_u32 s6, s91, 0
	v_ashrrev_i32_e32 v34, 3, v16
	v_and_b32_e32 v35, 0x70, v18
	v_lshl_or_b32 v217, v34, 11, v35
	s_and_b32 s37, s7, 0xffff
	s_mov_b32 s38, s30
	s_and_b32 s29, s6, 0xffff
	s_mov_b32 s39, s31
	s_waitcnt vmcnt(63) expcnt(7) lgkmcnt(15)
	s_barrier
	buffer_load_dwordx4 v[18:21], v216, s[28:31], 0 offen
	buffer_load_dwordx4 v[22:25], v216, s[28:31], s74 offen
	buffer_load_dwordx4 v[26:29], v217, s[36:39], 0 offen
	s_waitcnt vmcnt(6)
	v_lshlrev_b32_e32 v30, 16, v12
	v_and_b32_e32 v31, 0xffff0000, v12
	s_mov_b32 s8, 0x3e38aa3b
	v_lshlrev_b32_e32 v12, 16, v13
	v_and_b32_e32 v13, 0xffff0000, v13
	v_pk_mul_f32 v[12:13], v[12:13], s[8:9] op_sel_hi:[1,0]
	v_and_b32_e32 v200, 0xffffffe0, v17
	v_cvt_pk_bf16_f32 v147, v12, v13
	v_lshlrev_b32_e32 v12, 16, v14
	v_and_b32_e32 v13, 0xffff0000, v14
	v_pk_mul_f32 v[12:13], v[12:13], s[8:9] op_sel_hi:[1,0]
	v_and_b32_e32 v17, 0x3fffffc0, v16
	v_cvt_pk_bf16_f32 v148, v12, v13
	v_lshlrev_b32_e32 v12, 16, v15
	v_and_b32_e32 v13, 0xffff0000, v15
	v_pk_mul_f32 v[12:13], v[12:13], s[8:9] op_sel_hi:[1,0]
	s_add_i32 s6, 16, 0x12c00
	v_cvt_pk_bf16_f32 v149, v12, v13
	s_waitcnt vmcnt(5)
	v_lshlrev_b32_e32 v12, 16, v8
	v_and_b32_e32 v13, 0xffff0000, v8
	v_lshlrev_b32_e32 v8, 16, v9
	v_and_b32_e32 v9, 0xffff0000, v9
	v_pk_mul_f32 v[8:9], v[8:9], s[8:9] op_sel_hi:[1,0]
	v_and_b32_e32 v189, 31, v16
	v_cvt_pk_bf16_f32 v151, v8, v9
	v_lshlrev_b32_e32 v8, 16, v10
	v_and_b32_e32 v9, 0xffff0000, v10
	v_pk_mul_f32 v[8:9], v[8:9], s[8:9] op_sel_hi:[1,0]
	v_lshl_add_u32 v191, v17, 2, s6
	v_cvt_pk_bf16_f32 v152, v8, v9
	v_lshlrev_b32_e32 v8, 16, v11
	v_and_b32_e32 v9, 0xffff0000, v11
	v_pk_mul_f32 v[8:9], v[8:9], s[8:9] op_sel_hi:[1,0]
	s_movk_i32 s6, 0x90
	v_cvt_pk_bf16_f32 v153, v8, v9
	s_waitcnt vmcnt(4)
	v_lshlrev_b32_e32 v8, 16, v4
	v_and_b32_e32 v9, 0xffff0000, v4
	v_lshlrev_b32_e32 v4, 16, v5
	v_and_b32_e32 v5, 0xffff0000, v5
	v_pk_mul_f32 v[4:5], v[4:5], s[8:9] op_sel_hi:[1,0]
	v_pk_mul_f32 v[8:9], v[8:9], s[8:9] op_sel_hi:[1,0]
	v_cvt_pk_bf16_f32 v155, v4, v5
	v_lshlrev_b32_e32 v4, 16, v6
	v_and_b32_e32 v5, 0xffff0000, v6
	v_pk_mul_f32 v[4:5], v[4:5], s[8:9] op_sel_hi:[1,0]
	v_bfe_u32 v6, v33, 5, 2
	v_cvt_pk_bf16_f32 v156, v4, v5
	v_lshrrev_b32_e32 v5, 5, v16
	v_cvt_pk_bf16_f32 v154, v8, v9
	v_and_or_b32 v5, v5, s40, v6
	v_lshlrev_b32_e32 v6, 5, v32
	v_and_b32_e32 v8, 24, v33
	v_and_or_b32 v6, v6, s41, v8
	v_lshlrev_b32_e32 v6, 1, v6
	v_lshl_or_b32 v5, v5, 9, v6
	v_lshlrev_b32_e32 v4, 16, v7
	v_add_u32_e32 v218, 16, v5
	v_and_b32_e32 v5, 0xffff0000, v7
	v_mul_lo_u32 v6, v34, s6
	v_mul_u32_u24_e32 v220, 0x90, v189
	v_pk_mul_f32 v[4:5], v[4:5], s[8:9] op_sel_hi:[1,0]
	v_pk_mul_f32 v[12:13], v[12:13], s[8:9] op_sel_hi:[1,0]
	v_add3_u32 v219, v6, v35, 16
	v_add3_u32 v221, 16, v220, v198
	v_cvt_pk_bf16_f32 v157, v4, v5
	s_waitcnt vmcnt(3)
	v_lshlrev_b32_e32 v4, 16, v0
	v_and_b32_e32 v5, 0xffff0000, v0
	s_mov_b32 s6, 0x18000
	v_cvt_pk_bf16_f32 v150, v12, v13
	s_waitcnt vmcnt(0)
	s_waitcnt vmcnt(2)
	ds_write_b128 v218, v[18:21]
	s_waitcnt vmcnt(1)
	ds_write_b128 v218, v[22:25] offset:8192
	s_waitcnt vmcnt(0)
	ds_write_b128 v219, v[26:29] offset:49152
	s_waitcnt lgkmcnt(0)
	s_barrier
	ds_read_b128 v[8:11], v221 offset:49152
	v_pk_mul_f32 v[32:33], v[4:5], s[8:9] op_sel_hi:[1,0]
	ds_read_b128 v[4:7], v221 offset:53760
	ds_read_b128 v[12:15], v221 offset:49184
	buffer_load_dwordx4 v[48:51], v216, s[28:31], s75 offen
	buffer_load_dwordx4 v[52:55], v216, s[28:31], s6 offen
	buffer_load_dwordx4 v[56:59], v217, s[36:39], s31 offen
	v_pk_mul_f32 v[30:31], v[30:31], s[8:9] op_sel_hi:[1,0]
	v_lshlrev_b32_e32 v0, 16, v1
	v_cvt_pk_bf16_f32 v146, v30, v31
	v_and_b32_e32 v1, 0xffff0000, v1
	v_and_b32_e32 v64, 63, v16
	s_waitcnt lgkmcnt(2)
	v_mfma_f32_32x32x16_bf16 v[16:31], v[8:11], v[146:149], 0
	v_mul_f32_e64 v0, v0, s8
	v_mul_f32_e64 v1, v1, s8
	ds_read_b128 v[8:11], v221 offset:53792
	v_cvt_pk_bf16_f32 v159, v0, v1
	v_lshlrev_b32_e32 v0, 16, v2
	v_and_b32_e32 v1, 0xffff0000, v2
	v_cvt_pk_bf16_f32 v158, v32, v33
	v_pk_mul_f32 v[0:1], v[0:1], s[8:9] op_sel_hi:[1,0]
	s_waitcnt lgkmcnt(2)
	v_mfma_f32_32x32x16_bf16 v[32:47], v[4:7], v[146:149], 0
	v_cvt_pk_bf16_f32 v160, v0, v1
	v_lshlrev_b32_e32 v0, 16, v3
	v_and_b32_e32 v1, 0xffff0000, v3
	v_mul_f32_e64 v0, v0, s8
	v_mul_f32_e64 v1, v1, s8
	v_lshlrev_b32_e32 v4, 3, v64
	v_cvt_pk_bf16_f32 v161, v0, v1
	v_lshlrev_b32_e32 v0, 4, v64
	v_and_b32_e32 v5, 0xc0, v0
	v_lshlrev_b32_e32 v6, 1, v64
	v_and_or_b32 v5, v4, 24, v5
	v_and_b32_e32 v6, 32, v6
	v_and_b32_e32 v4, 0x100, v4
	s_cmp_lg_u32 16, -1
	s_waitcnt lgkmcnt(1)
	v_mfma_f32_32x32x16_bf16 v[16:31], v[12:15], v[150:153], v[16:31]
	v_or3_b32 v12, v5, v6, v4
	s_cselect_b32 s6, 16, 0
	v_add_u32_e32 v214, s6, v12
	s_mov_b32 s6, 0x28000
	ds_read_b128 v[0:3], v221 offset:49216
	s_mov_b32 s8, 0
	s_mov_b32 s9, s8
	s_waitcnt lgkmcnt(1)
	v_mfma_f32_32x32x16_bf16 v[32:47], v[8:11], v[150:153], v[32:47]
	ds_read_b128 v[4:7], v221 offset:53824
	ds_read_b128 v[8:11], v221 offset:49248
	ds_read_b128 v[60:63], v221 offset:53856
	buffer_load_dwordx4 v[162:165], v216, s[28:31], s31 offen
	buffer_load_dwordx4 v[166:169], v216, s[28:31], s6 offen
	buffer_load_dwordx4 v[170:173], v217, s[36:39], s76 offen
	s_waitcnt vmcnt(3)
	s_mov_b32 s10, s8
	s_mov_b32 s11, s8
	s_waitcnt lgkmcnt(3)
; #define SWRITE(b, i) do { STG_T() const int _sv = VSTV(), _sk = LDSK(); *(u32x4*)(V_lds + (b) * SHM_V + _sv) = sr_[i].vs0; *(u32x4*)(V_lds + (b) * SHM_V + _sv + 8192) = sr_[i].vs1; \
;     _Pragma("unroll") for (int _p = 0; _p < NP; ++_p) *(u32x4*)(K_lds + (b) * KT + _sk + _p * 128) = sr_[i].ks[_p]; } while (0)
; template <int NQK>
; __device__ __forceinline__ void qkt_mi(f32x16& p0, f32x16& p1, const char* Ks, const bf16x8* qr, int r32, int hi, const f32x16& minit) {
;   constexpr int KROW = NQK * 32 + 16;
; #pragma unroll
;   for (int d0 = 0; d0 < NQK; ++d0) { const int cb = (d0 * 16 + hi * 8) * 2;
;     bf16x8 b0 = *reinterpret_cast<const bf16x8*>(Ks + r32 * KROW + cb);
;     bf16x8 b1 = *reinterpret_cast<const bf16x8*>(Ks + (32 + r32) * KROW + cb);
;     if (d0 == 0) { p0 = __builtin_amdgcn_mfma_f32_32x32x16_bf16(b0, qr[0], minit, 0, 0, 0); p1 = __builtin_amdgcn_mfma_f32_32x32x16_bf16(b1, qr[0], minit, 0, 0, 0); }
;     else { p0 = __builtin_amdgcn_mfma_f32_32x32x16_bf16(b0, qr[d0], p0, 0, 0, 0); p1 = __builtin_amdgcn_mfma_f32_32x32x16_bf16(b1, qr[d0], p1, 0, 0, 0); } }
; }
; __device__ __forceinline__ void decide_mi(f32x16& p0, f32x16& p1, f32x16& minit, float& M, float& alpha, const float thr2, const bool first) {
;   float pmax = p0[0];
; #pragma unroll
;   for (int r = 1; r < 16; ++r) pmax = fmaxf(pmax, p0[r]);
; #pragma unroll
;   for (int r = 0; r < 16; ++r) pmax = fmaxf(pmax, p1[r]);
;   { auto rr = __builtin_amdgcn_permlane32_swap(__float_as_uint(pmax), __float_as_uint(pmax), false, false);
;     pmax = fmaxf(__uint_as_float(rr[0]), __uint_as_float(rr[1])); }
;   if (__builtin_expect(!first && __all(pmax <= thr2), 1)) { alpha = 1.f; }
;   else { const float delta = first ? pmax : fmaxf(pmax, 0.f); alpha = first ? 1.f : __builtin_amdgcn_exp2f(-delta); M += delta;
; #pragma unroll
;     for (int r = 0; r < 16; ++r) { p0[r] -= delta; p1[r] -= delta; minit[r] = -M; } }
; }
; template <int NQK, int SD, bool MI> ...
;     ...
;   if constexpr (MI) { qkt_mi<NQK>(pA0, pA1, K_lds, qr, r32, hi, minit); decide_mi(pA0, pA1, minit, Mref, alA, thr2, true);
; #pragma unroll
;     for (int r = 0; r < 16; ++r) pA0[r] = __builtin_amdgcn_exp2f(pA0[r]); }
;   else { qkt<NQK>(pA0, pA1, K_lds, qr, r32, hi); partialSM(pA0, pA1, m_reg, mnA, alA, C, thr); }
;   SLOAD(SO, 64); if constexpr (SD == 2) { if (2 < NT) SLOAD(SE, 2 * 64); }
;   SWAIT(); SWRITE(1, SO); __syncthreads();
	v_mfma_f32_32x32x16_bf16 v[16:31], v[0:3], v[154:157], v[16:31]
	s_mov_b32 s12, s8
	s_mov_b32 s13, s8
	s_mov_b32 s14, s8
	s_mov_b32 s15, s8
	s_mov_b32 s16, s8
	s_mov_b32 s17, s8
	s_mov_b32 s18, s8
	s_waitcnt lgkmcnt(2)
	v_mfma_f32_32x32x16_bf16 v[32:47], v[4:7], v[154:157], v[32:47]
	s_mov_b32 s19, s8
	s_mov_b32 s20, s8
	s_waitcnt vmcnt(5)
	ds_write_b128 v218, v[48:51] offset:16384
	s_waitcnt vmcnt(4)
	ds_write_b128 v218, v[52:55] offset:24576
	s_waitcnt vmcnt(3)
	ds_write_b128 v219, v[56:59] offset:58368
	s_waitcnt lgkmcnt(4)
	v_mfma_f32_32x32x16_bf16 v[16:31], v[8:11], v[158:161], v[16:31]
	s_mov_b32 s21, s8
	s_mov_b32 s22, s8
	s_mov_b32 s23, s8
	v_mov_b64_e32 v[0:1], s[8:9]
	v_mov_b64_e32 v[14:15], s[22:23]
	v_mov_b64_e32 v[2:3], s[10:11]
	v_mov_b64_e32 v[4:5], s[12:13]
	s_waitcnt lgkmcnt(3)
	v_mfma_f32_32x32x16_bf16 v[32:47], v[60:63], v[158:161], v[32:47]
	s_nop 2
	v_max_f32_e32 v60, v17, v17
	v_max_f32_e32 v61, v16, v16
	v_max_f32_e32 v60, v61, v60
	v_max3_f32 v60, v60, v18, v19
	v_max3_f32 v60, v60, v20, v21
	v_max3_f32 v60, v60, v22, v23
	v_max3_f32 v60, v60, v24, v25
	v_max3_f32 v60, v60, v26, v27
	v_max3_f32 v60, v60, v28, v29
	v_max3_f32 v60, v60, v30, v31
	v_max3_f32 v60, v60, v32, v33
	v_max3_f32 v60, v60, v34, v35
	v_max3_f32 v60, v60, v36, v37
	v_max3_f32 v60, v60, v38, v39
	v_max3_f32 v60, v60, v40, v41
	v_max3_f32 v60, v60, v42, v43
	v_max3_f32 v60, v60, v44, v45
	v_max3_f32 v60, v60, v46, v47
	v_mov_b32_e32 v61, v60
	s_nop 1
	v_permlane32_swap_b32_e32 v60, v61
	v_max_f32_e32 v48, v61, v61
	v_max_f32_e32 v49, v60, v60
	v_max_f32_e32 v48, v49, v48
	v_sub_f32_e32 v16, v16, v48
	v_exp_f32_e32 v175, v16
	v_sub_f32_e32 v16, v17, v48
	v_exp_f32_e32 v176, v16
	v_sub_f32_e32 v16, v18, v48
	v_exp_f32_e32 v177, v16
	v_sub_f32_e32 v16, v19, v48
	v_exp_f32_e32 v178, v16
	v_sub_f32_e32 v16, v20, v48
	v_exp_f32_e32 v179, v16
	v_sub_f32_e32 v16, v21, v48
	v_exp_f32_e32 v181, v16
	v_sub_f32_e32 v16, v22, v48
	v_exp_f32_e32 v183, v16
	v_sub_f32_e32 v16, v23, v48
	v_exp_f32_e32 v185, v16
	v_sub_f32_e32 v16, v24, v48
	v_exp_f32_e32 v180, v16
	v_sub_f32_e32 v16, v25, v48
	v_exp_f32_e32 v182, v16
	v_sub_f32_e32 v16, v26, v48
	v_exp_f32_e32 v184, v16
	v_sub_f32_e32 v16, v27, v48
	v_exp_f32_e32 v227, v16
	v_sub_f32_e32 v16, v28, v48
	v_exp_f32_e32 v228, v16
	v_sub_f32_e32 v16, v29, v48
	v_sub_f32_e32 v31, v31, v48
	v_exp_f32_e32 v229, v16
	v_sub_f32_e32 v16, v30, v48
	v_exp_f32_e32 v174, v31
	v_exp_f32_e32 v230, v16
	v_add_f32_e32 v222, 0, v48
	v_mov_b64_e32 v[6:7], s[14:15]
	v_mov_b64_e32 v[8:9], s[16:17]
	v_mov_b64_e32 v[10:11], s[18:19]
	v_mov_b64_e32 v[12:13], s[20:21]
	v_xor_b32_e32 v80, 0x80000000, v222
	v_sub_f32_e32 v111, v47, v48
	v_sub_f32_e32 v110, v46, v48
	v_sub_f32_e32 v109, v45, v48
	v_sub_f32_e32 v108, v44, v48
	v_sub_f32_e32 v107, v43, v48
	v_sub_f32_e32 v106, v42, v48
	v_sub_f32_e32 v105, v41, v48
	v_sub_f32_e32 v104, v40, v48
	v_sub_f32_e32 v103, v39, v48
	v_sub_f32_e32 v102, v38, v48
	v_sub_f32_e32 v101, v37, v48
	v_sub_f32_e32 v100, v36, v48
	v_sub_f32_e32 v99, v35, v48
	v_sub_f32_e32 v98, v34, v48
	v_sub_f32_e32 v97, v33, v48
	v_sub_f32_e32 v96, v32, v48
	v_mov_b64_e32 v[62:63], v[14:15]
	v_mov_b64_e32 v[46:47], v[14:15]
	v_mov_b64_e32 v[30:31], v[14:15]
	s_mov_b32 s58, 1
	s_mov_b32 s59, 2
	v_cmp_gt_u32_e64 s[6:7], 32, v64
	v_lshl_add_u32 v199, v189, 2, v191
	v_mov_b32_e32 v201, 0
	v_mov_b32_e32 v223, 1.0
	s_mov_b32 s12, 0x80000
	s_mov_b32 s13, 0x48000
	v_mov_b64_e32 v[60:61], v[12:13]
	v_mov_b64_e32 v[58:59], v[10:11]
	v_mov_b64_e32 v[56:57], v[8:9]
	v_mov_b64_e32 v[54:55], v[6:7]
	v_mov_b64_e32 v[52:53], v[4:5]
	v_mov_b64_e32 v[50:51], v[2:3]
	v_mov_b64_e32 v[48:49], v[0:1]
	v_mov_b64_e32 v[44:45], v[12:13]
	v_mov_b64_e32 v[42:43], v[10:11]
	v_mov_b64_e32 v[40:41], v[8:9]
	v_mov_b64_e32 v[38:39], v[6:7]
	v_mov_b64_e32 v[36:37], v[4:5]
	v_mov_b64_e32 v[34:35], v[2:3]
	v_mov_b64_e32 v[32:33], v[0:1]
	v_mov_b64_e32 v[28:29], v[12:13]
	v_mov_b64_e32 v[26:27], v[10:11]
	v_mov_b64_e32 v[24:25], v[8:9]
	v_mov_b64_e32 v[22:23], v[6:7]
	v_mov_b64_e32 v[20:21], v[4:5]
	v_mov_b64_e32 v[18:19], v[2:3]
	v_mov_b64_e32 v[16:17], v[0:1]
	s_mov_b32 s14, 1
	v_mov_b32_e32 v81, v80
	v_mov_b32_e32 v82, v80
	v_mov_b32_e32 v83, v80
	v_mov_b32_e32 v84, v80
	v_mov_b32_e32 v85, v80
	v_mov_b32_e32 v86, v80
	v_mov_b32_e32 v87, v80
	v_mov_b32_e32 v88, v80
	v_mov_b32_e32 v89, v80
	v_mov_b32_e32 v90, v80
	v_mov_b32_e32 v91, v80
	v_mov_b32_e32 v92, v80
	v_mov_b32_e32 v93, v80
	v_mov_b32_e32 v94, v80
	v_mov_b32_e32 v95, v80
	v_mov_b64_e32 v[64:65], v[80:81]
	v_mov_b64_e32 v[66:67], v[82:83]
	v_mov_b64_e32 v[68:69], v[84:85]
	v_mov_b64_e32 v[70:71], v[86:87]
	v_mov_b64_e32 v[72:73], v[88:89]
	v_mov_b64_e32 v[74:75], v[90:91]
	v_mov_b64_e32 v[76:77], v[92:93]
	v_mov_b64_e32 v[78:79], v[94:95]
	s_waitcnt lgkmcnt(0)
	s_barrier
; __device__ __forceinline__ void finishSM(f32x16& p0, f32x16& p1, float alpha, float& l_reg, bf16x8& pa0, bf16x8& pa1, bf16x8& pa2, bf16x8& pa3) {
; #pragma unroll
;   for (int r = 0; r < 16; ++r) p1[r] = __builtin_amdgcn_exp2f(p1[r]);
;   float ps = 0;
; #pragma unroll
;   for (int r = 0; r < 16; ++r) ps += p0[r];
; #pragma unroll
;   for (int r = 0; r < 16; ++r) ps += p1[r];
;   { auto rr = __builtin_amdgcn_permlane32_swap(__float_as_uint(ps), __float_as_uint(ps), false, false);
;     ps = __uint_as_float(rr[0]) + __uint_as_float(rr[1]); }
;   l_reg = l_reg * alpha + ps;
;     ...
;   PK4(p0, 0, pa0); PK4(p0, 8, pa1); PK4(p1, 0, pa2); PK4(p1, 8, pa3);
;     ...
; }
; template <int NQK>
; __device__ __forceinline__ void qkt(f32x16& p0, f32x16& p1, const char* Ks, const bf16x8* qr, int r32, int hi) {
;   constexpr int KROW = NQK * 32 + 16;
;   p0 = f32x16{}; p1 = f32x16{};
; #pragma unroll
;   for (int d0 = 0; d0 < NQK; ++d0) { const int cb = (d0 * 16 + hi * 8) * 2;
;     bf16x8 b0 = *reinterpret_cast<const bf16x8*>(Ks + r32 * KROW + cb);
;     bf16x8 b1 = *reinterpret_cast<const bf16x8*>(Ks + (32 + r32) * KROW + cb);
;     p0 = __builtin_amdgcn_mfma_f32_32x32x16_bf16(b0, qr[d0], p0, 0, 0, 0);
;     p1 = __builtin_amdgcn_mfma_f32_32x32x16_bf16(b1, qr[d0], p1, 0, 0, 0); }
; }
; template <int NQK>
; __device__ __forceinline__ void qkt_mi(f32x16& p0, f32x16& p1, const char* Ks, const bf16x8* qr, int r32, int hi, const f32x16& minit) {
;   constexpr int KROW = NQK * 32 + 16;
; #pragma unroll
;   for (int d0 = 0; d0 < NQK; ++d0) { const int cb = (d0 * 16 + hi * 8) * 2;
;     bf16x8 b0 = *reinterpret_cast<const bf16x8*>(Ks + r32 * KROW + cb);
;     bf16x8 b1 = *reinterpret_cast<const bf16x8*>(Ks + (32 + r32) * KROW + cb);
;     if (d0 == 0) { p0 = __builtin_amdgcn_mfma_f32_32x32x16_bf16(b0, qr[0], minit, 0, 0, 0); p1 = __builtin_amdgcn_mfma_f32_32x32x16_bf16(b1, qr[0], minit, 0, 0, 0); }
;     else { p0 = __builtin_amdgcn_mfma_f32_32x32x16_bf16(b0, qr[d0], p0, 0, 0, 0); p1 = __builtin_amdgcn_mfma_f32_32x32x16_bf16(b1, qr[d0], p1, 0, 0, 0); } }
; }
; __device__ __forceinline__ void decide_mi(f32x16& p0, f32x16& p1, f32x16& minit, float& M, float& alpha, const float thr2, const bool first) {
;   float pmax = p0[0];
; #pragma unroll
;   for (int r = 1; r < 16; ++r) pmax = fmaxf(pmax, p0[r]);
; #pragma unroll
;   for (int r = 0; r < 16; ++r) pmax = fmaxf(pmax, p1[r]);
.LBB0_1286:
	s_mov_b32 s15, s58
	s_mov_b32 s58, s8
	s_mul_i32 s8, s15, 0x2400
	v_add_u32_e32 v215, s8, v221
	ds_read_b128 v[232:235], v215 offset:53760
	ds_read_b128 v[112:115], v215 offset:49152
	ds_read_b128 v[236:239], v215 offset:49184
	v_exp_f32_e32 v96, v96
	v_exp_f32_e32 v97, v97
	v_exp_f32_e32 v99, v99
	s_waitcnt lgkmcnt(1)
	v_mfma_f32_32x32x16_bf16 v[128:143], v[112:115], v[146:149], v[80:95]
	s_waitcnt lgkmcnt(0)
	v_mfma_f32_32x32x16_bf16 v[128:143], v[236:239], v[150:153], v[128:143]
	v_exp_f32_e32 v100, v100
	v_exp_f32_e32 v101, v101
	v_exp_f32_e32 v102, v102
	v_exp_f32_e32 v103, v103
	v_mfma_f32_32x32x16_bf16 v[112:127], v[232:235], v[146:149], v[80:95]
	ds_read_b128 v[232:235], v215 offset:53792
	s_waitcnt lgkmcnt(0)
	v_mfma_f32_32x32x16_bf16 v[112:127], v[232:235], v[150:153], v[112:127]
	ds_read_b128 v[232:235], v215 offset:53824
	ds_read_b128 v[236:239], v215 offset:49216
	s_waitcnt lgkmcnt(0)
	v_mfma_f32_32x32x16_bf16 v[128:143], v[236:239], v[154:157], v[128:143]
	v_mfma_f32_32x32x16_bf16 v[112:127], v[232:235], v[154:157], v[112:127]
	ds_read_b128 v[232:235], v215 offset:53856
	ds_read_b128 v[236:239], v215 offset:49248
	v_exp_f32_e32 v215, v98
	v_exp_f32_e32 v98, v104
	v_exp_f32_e32 v104, v105
	v_exp_f32_e32 v105, v106
	v_exp_f32_e32 v106, v107
	v_exp_f32_e32 v107, v108
	v_exp_f32_e32 v108, v109
	v_exp_f32_e32 v109, v110
	v_exp_f32_e32 v110, v111
	v_add_f32_e32 v111, 0, v175
	v_add_f32_e32 v111, v176, v111
	v_add_f32_e32 v111, v177, v111
	v_add_f32_e32 v111, v178, v111
	v_add_f32_e32 v111, v179, v111
	v_add_f32_e32 v111, v181, v111
	v_add_f32_e32 v111, v183, v111
	v_add_f32_e32 v111, v185, v111
	v_add_f32_e32 v111, v180, v111
	v_add_f32_e32 v111, v182, v111
	v_add_f32_e32 v111, v184, v111
	v_add_f32_e32 v111, v227, v111
	v_add_f32_e32 v111, v228, v111
	v_add_f32_e32 v111, v229, v111
	v_add_f32_e32 v111, v230, v111
	v_add_f32_e32 v111, v174, v111
	v_add_f32_e32 v111, v96, v111
	v_add_f32_e32 v111, v97, v111
	v_add_f32_e32 v111, v215, v111
	v_add_f32_e32 v111, v99, v111
	v_add_f32_e32 v111, v100, v111
	v_add_f32_e32 v111, v101, v111
	v_add_f32_e32 v111, v102, v111
	s_waitcnt lgkmcnt(0)
	v_mfma_f32_32x32x16_bf16 v[128:143], v[236:239], v[158:161], v[128:143]
	v_add_f32_e32 v111, v103, v111
	v_add_f32_e32 v111, v98, v111
	v_add_f32_e32 v111, v104, v111
	v_add_f32_e32 v111, v105, v111
	v_add_f32_e32 v111, v106, v111
	v_add_f32_e32 v111, v107, v111
	v_add_f32_e32 v111, v108, v111
	v_add_f32_e32 v111, v109, v111
	v_add_f32_e32 v224, v110, v111
	s_nop 2
	v_max_f32_e32 v111, v129, v129
	v_max_f32_e32 v226, v128, v128
	v_mfma_f32_32x32x16_bf16 v[112:127], v[232:235], v[158:161], v[112:127]
	v_max_f32_e32 v111, v226, v111
	v_max3_f32 v111, v111, v130, v131
	v_max3_f32 v111, v111, v132, v133
	v_max3_f32 v111, v111, v134, v135
	v_max3_f32 v111, v111, v136, v137
	v_max3_f32 v111, v111, v138, v139
	v_max3_f32 v111, v111, v140, v141
	v_max3_f32 v111, v111, v142, v143
	s_nop 3
	v_max3_f32 v111, v111, v112, v113
	v_max3_f32 v111, v111, v114, v115
	v_max3_f32 v111, v111, v116, v117
	v_max3_f32 v111, v111, v118, v119
	v_max3_f32 v111, v111, v120, v121
	v_max3_f32 v111, v111, v122, v123
	v_max3_f32 v111, v111, v124, v125
	v_max3_f32 v111, v111, v126, v127
	v_mov_b32_e32 v226, v111
	s_nop 1
	v_permlane32_swap_b32_e32 v111, v226
	v_max_f32_e32 v226, v226, v226
	v_max_f32_e32 v111, v111, v111
	v_max_f32_e32 v111, v111, v226
	v_mov_b32_e32 v225, v224
	v_cmp_ge_f32_e32 vcc, s42, v111
	s_nop 0
	v_permlane32_swap_b32_e32 v224, v225
	s_cmp_eq_u64 vcc, exec
	s_cbranch_scc0 .LBB0_1301
	v_mov_b32_e32 v226, 1.0
